# P2 fused merge: u[t-1], u[t-2] rows taken from neighbouring lanes' u[t] registers (DPP wave shift) + 4-lane loads of the two rows above the block; 8 scattered loads per chunk removed
# speedup vs baseline: 1.0173x; 1.0052x over previous
.LBB0_728:
	s_or_b64 exec, exec, s[12:13]
	v_readfirstlane_b32 s14, v0
	s_cmp_ge_i32 s14, s22
	s_mov_b64 s[12:13], -1
	s_cbranch_scc1 .LBB0_723
	s_cmp_ge_i32 s14, s21
	v_lshlrev_b32_e32 v92, 1, v138
	v_mbcnt_hi_u32_b32 v102, -1, v220
	s_cbranch_scc0 .LBB0_731
	s_sub_i32 s12, s14, s21
	s_and_b32 s15, s12, 3
	s_lshl_b32 s13, s15, 5
	v_or_b32_e32 v0, s13, v154
	s_lshr_b32 s12, s12, 2
	v_ashrrev_i32_e32 v1, 31, v0
	v_readlane_b32 s24, v254, 54
	v_lshlrev_b64 v[84:85], 12, v[0:1]
	v_readlane_b32 s25, v254, 55
	s_add_i32 s12, s12, s23
	v_mov_b32_e32 v93, v131
	v_lshl_add_u64 v[0:1], s[24:25], 0, v[84:85]
	s_lshl_b32 s24, s12, 7
	s_mov_b32 s25, s92
	v_lshl_add_u64 v[0:1], v[0:1], 0, s[24:25]
	v_lshl_add_u64 v[90:91], v[0:1], 0, v[92:93]
	global_load_dwordx4 v[68:71], v[90:91], off
	global_load_dwordx4 v[64:67], v[90:91], off offset:32
	s_add_i32 s93, s15, 1
	v_lshl_or_b32 v4, s93, 5, v136
	v_mad_u32_u24 v94, v4, s16, v129
	ds_read_b128 v[16:19], v94
	ds_read_b128 v[76:79], v94 offset:32
	s_add_i32 s94, s15, 2
	v_lshl_or_b32 v20, s94, 5, v136
	v_mad_u32_u24 v95, v20, s16, v129
	v_or_b32_e32 v2, s13, v136
	s_add_i32 s95, s15, 3
	v_mad_u32_u24 v93, v2, s16, v129
	v_lshl_or_b32 v20, s95, 5, v136
	ds_read_b128 v[0:3], v93
	ds_read_b128 v[72:75], v93 offset:32
	v_mad_u32_u24 v96, v20, s16, v129
	s_mov_b32 s13, s92
	v_readlane_b32 s56, v254, 22
	s_or_b32 s24, s15, 4
	s_lshl_b64 vcc, s[12:13], 2
	v_readlane_b32 s58, v254, 24
	v_readlane_b32 s59, v254, 25
	s_add_u32 vcc_lo, s58, vcc_lo
	s_addc_u32 vcc_hi, s59, vcc_hi
	s_cmp_eq_u32 s15, 3
	v_readlane_b32 s57, v254, 23
	v_readlane_b32 s56, v255, 4
	v_readlane_b32 s57, v255, 5
	v_readlane_b32 s60, v254, 26
	v_readlane_b32 s61, v254, 27
	v_readlane_b32 s62, v254, 28
	v_readlane_b32 s63, v254, 29
	v_readlane_b32 s64, v254, 30
	v_readlane_b32 s65, v254, 31
	v_readlane_b32 s66, v254, 32
	v_readlane_b32 s67, v254, 33
	v_readlane_b32 s68, v254, 34
	v_readlane_b32 s69, v254, 35
	v_readlane_b32 s70, v254, 36
	v_readlane_b32 s71, v254, 37
	s_waitcnt vmcnt(1) lgkmcnt(3)
	v_mfma_f32_32x32x16_bf16 v[48:63], v[16:19], v[68:71], 0
	ds_read_b128 v[16:19], v95
	ds_read_b128 v[80:83], v95 offset:32
	s_waitcnt lgkmcnt(1)
	v_mfma_f32_32x32x16_bf16 v[32:47], v[16:19], v[68:71], 0
	ds_read_b128 v[16:19], v96
	ds_read_b128 v[86:89], v96 offset:32
	s_waitcnt vmcnt(0)
	v_mfma_f32_32x32x16_bf16 v[48:63], v[76:79], v[64:67], v[48:63]
	global_load_dwordx4 v[76:79], v[90:91], off offset:64
	v_mfma_f32_32x32x16_bf16 v[0:15], v[0:3], v[68:71], 0
	v_mfma_f32_32x32x16_bf16 v[0:15], v[72:75], v[64:67], v[0:15]
	global_load_dwordx4 v[72:75], v[90:91], off offset:96
	s_waitcnt lgkmcnt(1)
	v_mfma_f32_32x32x16_bf16 v[16:31], v[16:19], v[68:71], 0
	v_mfma_f32_32x32x16_bf16 v[32:47], v[80:83], v[64:67], v[32:47]
	s_waitcnt lgkmcnt(0)
	v_mfma_f32_32x32x16_bf16 v[16:31], v[86:89], v[64:67], v[16:31]
	ds_read_b128 v[86:89], v93 offset:64
	ds_read_b128 v[80:83], v93 offset:96
	s_waitcnt vmcnt(1) lgkmcnt(1)
	v_mfma_f32_32x32x16_bf16 v[0:15], v[86:89], v[76:79], v[0:15]
	ds_read_b128 v[86:89], v94 offset:64
	ds_read_b128 v[98:101], v94 offset:96
	s_waitcnt lgkmcnt(1)
	v_mfma_f32_32x32x16_bf16 v[48:63], v[86:89], v[76:79], v[48:63]
	ds_read_b128 v[86:89], v95 offset:64
	ds_read_b128 v[104:107], v95 offset:96
	s_waitcnt lgkmcnt(1)
	v_mfma_f32_32x32x16_bf16 v[32:47], v[86:89], v[76:79], v[32:47]
	ds_read_b128 v[86:89], v96 offset:64
	ds_read_b128 v[112:115], v96 offset:96
	global_load_dword v96, v131, vcc
	s_mov_b32 s62, 0x6e80000
	s_mov_b32 s63, 0
	s_mov_b32 s64, 0x4c80000
	s_mov_b32 s65, 0
	s_mov_b32 s66, 0x2a80000
	s_mov_b32 s67, 0
	v_lshl_add_u64 v[190:191], v[90:91], 0, s[62:63]
	global_load_dwordx4 v[222:225], v[190:191], off
	global_load_dwordx4 v[226:229], v[190:191], off offset:32
	global_load_dwordx4 v[230:233], v[190:191], off offset:64
	global_load_dwordx4 v[234:237], v[190:191], off offset:96
	v_lshl_add_u64 v[190:191], v[90:91], 0, s[64:65]
	global_load_dwordx4 v[238:241], v[190:191], off
	global_load_dwordx4 v[242:245], v[190:191], off offset:32
	global_load_dwordx4 v[246:249], v[190:191], off offset:64
	global_load_dwordx4 v[250:253], v[190:191], off offset:96
	v_lshl_add_u64 v[190:191], v[90:91], 0, s[66:67]
	global_load_dwordx4 v[182:185], v[190:191], off
	global_load_dwordx4 v[186:189], v[190:191], off offset:32
	global_load_dwordx4 v[202:205], v[190:191], off offset:64
	global_load_dwordx4 v[206:209], v[190:191], off offset:96
	s_mov_b32 s66, 0x2a7e000
	s_mov_b32 s70, 3
	s_mov_b32 s71, 3
	s_mov_b64 s[68:69], exec
	v_lshl_add_u64 v[190:191], v[90:91], 0, s[66:67]
	s_mov_b64 exec, s[70:71]
	global_load_dwordx4 v[144:147], v[190:191], off
	global_load_dwordx4 v[148:151], v[190:191], off offset:32
	global_load_dwordx4 v[192:195], v[190:191], off offset:64
	global_load_dwordx4 v[196:199], v[190:191], off offset:96
	s_mov_b64 exec, s[68:69]
	s_cselect_b64 vcc, -1, 0
	s_or_b64 vcc, s[8:9], vcc
	s_xor_b32 s13, s15, 2
	s_cmp_lt_u32 s13, 2
	s_waitcnt lgkmcnt(1)
	v_mfma_f32_32x32x16_bf16 v[16:31], v[86:89], v[76:79], v[16:31]
	s_waitcnt vmcnt(17)
	v_mfma_f32_32x32x16_bf16 v[48:63], v[98:101], v[72:75], v[48:63]
	v_mfma_f32_32x32x16_bf16 v[32:47], v[104:107], v[72:75], v[32:47]
	s_nop 10
	v_cndmask_b32_e32 v48, v179, v48, vcc
	v_cndmask_b32_e32 v49, v179, v49, vcc
	v_cndmask_b32_e32 v50, v179, v50, vcc
	v_cndmask_b32_e32 v51, v179, v51, vcc
	v_cndmask_b32_e32 v52, v179, v52, vcc
	v_cndmask_b32_e32 v53, v179, v53, vcc
	v_cndmask_b32_e32 v54, v179, v54, vcc
	s_waitcnt lgkmcnt(0)
	v_mfma_f32_32x32x16_bf16 v[16:31], v[112:115], v[72:75], v[16:31]
	v_cndmask_b32_e32 v55, v179, v55, vcc
	v_cndmask_b32_e32 v56, v179, v56, vcc
	v_cndmask_b32_e32 v57, v179, v57, vcc
	v_cndmask_b32_e32 v58, v179, v58, vcc
	v_cndmask_b32_e32 v59, v179, v59, vcc
	v_cndmask_b32_e32 v60, v179, v60, vcc
	v_cndmask_b32_e32 v61, v179, v61, vcc
	v_cndmask_b32_e32 v62, v179, v62, vcc
	v_cndmask_b32_e32 v116, v179, v63, vcc
	s_cselect_b64 vcc, -1, 0
	s_or_b64 vcc, s[8:9], vcc
	s_or_b32 s13, s15, s20
	s_cmp_eq_u32 s13, 0
	v_cndmask_b32_e32 v117, v179, v32, vcc
	v_cndmask_b32_e32 v118, v179, v33, vcc
	v_cndmask_b32_e32 v119, v179, v34, vcc
	v_cndmask_b32_e32 v120, v179, v35, vcc
	v_cndmask_b32_e32 v121, v179, v36, vcc
	v_cndmask_b32_e32 v122, v179, v37, vcc
	v_cndmask_b32_e32 v123, v179, v38, vcc
	v_cndmask_b32_e32 v130, v179, v39, vcc
	v_cndmask_b32_e32 v63, v179, v40, vcc
	v_cndmask_b32_e32 v111, v179, v41, vcc
	v_cndmask_b32_e32 v110, v179, v42, vcc
	v_cndmask_b32_e32 v109, v179, v43, vcc
	v_cndmask_b32_e32 v108, v179, v44, vcc
	v_cndmask_b32_e32 v107, v179, v45, vcc
	v_cndmask_b32_e32 v106, v179, v46, vcc
	v_cndmask_b32_e32 v105, v179, v47, vcc
	s_cselect_b64 vcc, -1, 0
	v_cndmask_b32_e32 v103, v17, v179, vcc
	v_and_b32_e32 v17, 64, v102
	v_cndmask_b32_e32 v104, v16, v179, vcc
	v_xor_b32_e32 v16, 32, v102
	v_add_u32_e32 v17, 64, v17
	v_cndmask_b32_e32 v101, v18, v179, vcc
	v_cndmask_b32_e32 v100, v19, v179, vcc
	v_cndmask_b32_e32 v99, v20, v179, vcc
	v_cndmask_b32_e32 v98, v21, v179, vcc
	v_cndmask_b32_e32 v97, v22, v179, vcc
	v_cndmask_b32_e32 v95, v23, v179, vcc
	v_cndmask_b32_e32 v94, v24, v179, vcc
	v_cndmask_b32_e32 v93, v25, v179, vcc
	v_cndmask_b32_e32 v91, v26, v179, vcc
	v_cndmask_b32_e32 v90, v27, v179, vcc
	v_cndmask_b32_e32 v86, v28, v179, vcc
	v_cndmask_b32_e32 v87, v29, v179, vcc
	v_cndmask_b32_e32 v88, v30, v179, vcc
	v_cndmask_b32_e32 v89, v31, v179, vcc
	v_cmp_lt_i32_e32 vcc, v16, v17
	v_mfma_f32_32x32x16_bf16 v[0:15], v[80:83], v[72:75], v[0:15]
	s_mov_b32 s13, 0x3fb8aa3b
	v_cndmask_b32_e32 v44, v102, v16, vcc
	v_lshl_or_b32 v16, s24, 5, v136
	v_mad_u32_u24 v40, v16, s16, v129
	ds_read_b128 v[16:19], v40
	ds_read_b128 v[32:35], v40 offset:32
	ds_read_b128 v[36:39], v40 offset:64
	ds_read_b128 v[40:43], v40 offset:96
	v_lshlrev_b32_e32 v112, 2, v44
	s_waitcnt lgkmcnt(3)
	v_mfma_f32_32x32x16_bf16 v[16:31], v[16:19], v[68:71], 0
	s_nop 0
	v_cndmask_b32_e64 v0, v179, v0, s[26:27]
	v_cndmask_b32_e64 v1, v179, v1, s[28:29]
	v_max3_f32 v45, v0, s17, v1
	v_cndmask_b32_e64 v2, v179, v2, s[30:31]
	v_cndmask_b32_e64 v3, v179, v3, s[34:35]
	v_cndmask_b32_e64 v4, v179, v4, s[36:37]
	v_cndmask_b32_e64 v5, v179, v5, s[38:39]
	s_waitcnt lgkmcnt(2)
	v_mfma_f32_32x32x16_bf16 v[16:31], v[32:35], v[64:67], v[16:31]
	v_max3_f32 v32, v45, v2, v3
	v_max3_f32 v32, v32, v4, v5
	v_cndmask_b32_e64 v6, v179, v6, s[96:97]
	v_cndmask_b32_e64 v7, v179, v7, s[2:3]
	v_max3_f32 v32, v32, v6, v7
	v_cndmask_b32_e64 v8, v179, v8, s[72:73]
	v_cndmask_b32_e64 v9, v179, v9, s[74:75]
	s_waitcnt lgkmcnt(1)
	v_mfma_f32_32x32x16_bf16 v[16:31], v[36:39], v[76:79], v[16:31]
	v_max3_f32 v32, v32, v8, v9
	v_cndmask_b32_e64 v34, v179, v10, s[76:77]
	v_cndmask_b32_e64 v11, v179, v11, s[78:79]
	v_max3_f32 v10, v32, v34, v11
	v_cndmask_b32_e64 v12, v179, v12, s[80:81]
	v_cndmask_b32_e64 v13, v179, v13, s[82:83]
	v_max3_f32 v10, v10, v12, v13
	s_waitcnt lgkmcnt(0)
	v_mfma_f32_32x32x16_bf16 v[16:31], v[40:43], v[72:75], v[16:31]
	v_cndmask_b32_e64 v14, v179, v14, s[84:85]
	v_cndmask_b32_e64 v15, v179, v15, s[86:87]
	v_max3_f32 v10, v10, v14, v15
	v_max3_f32 v10, v10, v48, v49
	v_max3_f32 v10, v10, v50, v51
	v_max3_f32 v10, v10, v52, v53
	v_max3_f32 v10, v10, v54, v55
	s_nop 4
	v_cndmask_b32_e64 v16, v16, v179, s[56:57]
	v_readlane_b32 s56, v255, 34
	v_readlane_b32 s57, v255, 35
	v_max3_f32 v10, v10, v56, v57
	v_max3_f32 v10, v10, v58, v59
	v_cndmask_b32_e64 v17, v179, v17, s[56:57]
	v_readlane_b32 s56, v255, 8
	v_readlane_b32 s57, v255, 9
	v_max3_f32 v10, v10, v60, v61
	v_max3_f32 v10, v10, v62, v116
	v_cndmask_b32_e64 v18, v18, v179, s[56:57]
	v_readlane_b32 s56, v255, 10
	v_readlane_b32 s57, v255, 11
	v_max3_f32 v10, v10, v117, v118
	v_max3_f32 v10, v10, v119, v120
	v_cndmask_b32_e64 v19, v19, v179, s[56:57]
	v_readlane_b32 s56, v255, 12
	v_readlane_b32 s57, v255, 13
	v_max3_f32 v10, v10, v121, v122
	v_max3_f32 v10, v10, v123, v130
	v_cndmask_b32_e64 v20, v20, v179, s[56:57]
	v_readlane_b32 s56, v255, 14
	v_readlane_b32 s57, v255, 15
	v_max3_f32 v10, v10, v63, v111
	v_max3_f32 v10, v10, v110, v109
	v_cndmask_b32_e64 v21, v21, v179, s[56:57]
	v_readlane_b32 s56, v255, 16
	v_readlane_b32 s57, v255, 17
	v_max3_f32 v10, v10, v108, v107
	v_max3_f32 v10, v10, v106, v105
	v_cndmask_b32_e64 v22, v22, v179, s[56:57]
	v_readlane_b32 s56, v255, 18
	v_readlane_b32 s57, v255, 19
	v_max3_f32 v10, v10, v104, v103
	v_max3_f32 v10, v10, v101, v100
	v_cndmask_b32_e64 v23, v23, v179, s[56:57]
	v_readlane_b32 s56, v255, 20
	v_readlane_b32 s57, v255, 21
	v_max3_f32 v10, v10, v99, v98
	v_max3_f32 v10, v10, v97, v95
	v_cndmask_b32_e64 v24, v24, v179, s[56:57]
	v_readlane_b32 s56, v255, 22
	v_readlane_b32 s57, v255, 23
	v_max3_f32 v10, v10, v94, v93
	v_max3_f32 v10, v10, v91, v90
	v_cndmask_b32_e64 v25, v25, v179, s[56:57]
	v_readlane_b32 s56, v255, 24
	v_readlane_b32 s57, v255, 25
	v_max3_f32 v10, v10, v86, v87
	v_max3_f32 v10, v10, v88, v89
	v_cndmask_b32_e64 v26, v26, v179, s[56:57]
	v_readlane_b32 s56, v255, 26
	v_readlane_b32 s57, v255, 27
	v_max3_f32 v10, v10, v16, v17
	v_max3_f32 v10, v10, v18, v19
	v_cndmask_b32_e64 v27, v27, v179, s[56:57]
	v_readlane_b32 s56, v255, 28
	v_readlane_b32 s57, v255, 29
	v_max3_f32 v10, v10, v20, v21
	v_max3_f32 v10, v10, v22, v23
	v_cndmask_b32_e64 v28, v28, v179, s[56:57]
	v_readlane_b32 s56, v255, 30
	v_readlane_b32 s57, v255, 31
	v_max3_f32 v10, v10, v24, v25
	v_max3_f32 v10, v10, v26, v27
	v_cndmask_b32_e64 v29, v29, v179, s[56:57]
	v_readlane_b32 s56, v255, 32
	v_readlane_b32 s57, v255, 33
	v_max3_f32 v10, v10, v28, v29
	s_waitcnt vmcnt(16)
	v_mul_f32_e32 v33, 0x3fb8aa3b, v96
	v_cndmask_b32_e64 v30, v30, v179, s[56:57]
	v_readlane_b32 s56, v255, 2
	v_readlane_b32 s57, v255, 3
	v_lshl_add_u32 v115, s93, 6, v139
	v_lshl_or_b32 v114, s12, 6, v137
	v_cndmask_b32_e64 v31, v31, v179, s[56:57]
	v_max3_f32 v10, v10, v30, v31
	ds_bpermute_b32 v32, v112, v10
	s_waitcnt lgkmcnt(0)
	v_max_f32_e32 v32, v32, v32
	v_max_f32_e32 v10, v10, v32
	v_mul_f32_e32 v10, 0x3e38aa3b, v10
	v_max_f32_e32 v10, v10, v33
	v_fma_f32 v0, v0, s18, -v10
	v_exp_f32_e32 v0, v0
	v_fma_f32 v1, v1, s18, -v10
	v_exp_f32_e32 v1, v1
	v_fma_f32 v2, v2, s18, -v10
	v_exp_f32_e32 v2, v2
	v_fma_f32 v3, v3, s18, -v10
	v_exp_f32_e32 v3, v3
	v_fma_f32 v4, v4, s18, -v10
	v_add_f32_e32 v32, 0, v0
	v_exp_f32_e32 v4, v4
	v_fma_f32 v5, v5, s18, -v10
	v_add_f32_e32 v32, v1, v32
	v_exp_f32_e32 v5, v5
	v_fma_f32 v6, v6, s18, -v10
	v_add_f32_e32 v32, v2, v32
	v_exp_f32_e32 v6, v6
	v_fma_f32 v7, v7, s18, -v10
	v_add_f32_e32 v32, v3, v32
	v_exp_f32_e32 v7, v7
	v_add_f32_e32 v32, v4, v32
	v_add_f32_e32 v32, v5, v32
	v_add_f32_e32 v32, v6, v32
	v_fma_f32 v8, v8, s18, -v10
	v_add_f32_e32 v36, v7, v32
	v_exp_f32_e32 v32, v8
	v_fma_f32 v8, v9, s18, -v10
	v_exp_f32_e32 v33, v8
	v_fma_f32 v8, v34, s18, -v10
	v_exp_f32_e32 v34, v8
	v_fma_f32 v8, v11, s18, -v10
	v_exp_f32_e32 v35, v8
	v_fma_f32 v9, v12, s18, -v10
	v_add_f32_e32 v8, v32, v36
	v_exp_f32_e32 v36, v9
	v_fma_f32 v9, v13, s18, -v10
	v_add_f32_e32 v8, v33, v8
	v_exp_f32_e32 v37, v9
	v_fma_f32 v9, v14, s18, -v10
	v_add_f32_e32 v8, v34, v8
	v_exp_f32_e32 v38, v9
	v_fma_f32 v9, v15, s18, -v10
	v_add_f32_e32 v8, v35, v8
	v_exp_f32_e32 v40, v9
	v_fma_f32 v9, v48, s18, -v10
	v_add_f32_e32 v8, v36, v8
	v_exp_f32_e32 v39, v9
	v_fma_f32 v9, v49, s18, -v10
	v_add_f32_e32 v8, v37, v8
	v_exp_f32_e32 v41, v9
	v_fma_f32 v9, v50, s18, -v10
	v_add_f32_e32 v8, v38, v8
	v_exp_f32_e32 v42, v9
	v_fma_f32 v9, v51, s18, -v10
	v_add_f32_e32 v8, v40, v8
	v_exp_f32_e32 v43, v9
	v_fma_f32 v9, v52, s18, -v10
	v_add_f32_e32 v8, v39, v8
	v_exp_f32_e32 v44, v9
	v_fma_f32 v9, v53, s18, -v10
	v_add_f32_e32 v8, v41, v8
	v_exp_f32_e32 v45, v9
	v_fma_f32 v9, v54, s18, -v10
	v_add_f32_e32 v8, v42, v8
	v_exp_f32_e32 v46, v9
	v_fma_f32 v9, v55, s18, -v10
	v_add_f32_e32 v8, v43, v8
	v_exp_f32_e32 v48, v9
	v_fma_f32 v9, v56, s18, -v10
	v_add_f32_e32 v8, v44, v8
	v_exp_f32_e32 v47, v9
	v_fma_f32 v9, v57, s18, -v10
	v_add_f32_e32 v8, v45, v8
	v_exp_f32_e32 v49, v9
	v_fma_f32 v9, v58, s18, -v10
	v_add_f32_e32 v8, v46, v8
	v_exp_f32_e32 v50, v9
	v_fma_f32 v9, v59, s18, -v10
	v_add_f32_e32 v8, v48, v8
	v_exp_f32_e32 v51, v9
	v_fma_f32 v9, v60, s18, -v10
	v_add_f32_e32 v8, v47, v8
	v_exp_f32_e32 v52, v9
	v_fma_f32 v9, v61, s18, -v10
	v_add_f32_e32 v8, v49, v8
	v_exp_f32_e32 v53, v9
	v_fma_f32 v9, v62, s18, -v10
	v_add_f32_e32 v8, v50, v8
	v_exp_f32_e32 v54, v9
	v_fma_f32 v9, v116, s18, -v10
	v_add_f32_e32 v8, v51, v8
	v_exp_f32_e32 v56, v9
	v_fma_f32 v9, v117, s18, -v10
	v_add_f32_e32 v8, v52, v8
	v_exp_f32_e32 v55, v9
	v_fma_f32 v9, v118, s18, -v10
	v_add_f32_e32 v8, v53, v8
	v_exp_f32_e32 v57, v9
	v_fma_f32 v9, v119, s18, -v10
	v_add_f32_e32 v8, v54, v8
	v_exp_f32_e32 v58, v9
	v_fma_f32 v9, v120, s18, -v10
	v_add_f32_e32 v8, v56, v8
	v_exp_f32_e32 v59, v9
	v_fma_f32 v9, v121, s18, -v10
	v_add_f32_e32 v8, v55, v8
	v_exp_f32_e32 v60, v9
	v_fma_f32 v9, v122, s18, -v10
	v_add_f32_e32 v8, v57, v8
	v_exp_f32_e32 v61, v9
	v_fma_f32 v9, v123, s18, -v10
	v_add_f32_e32 v8, v58, v8
	v_exp_f32_e32 v62, v9
	v_fma_f32 v9, v130, s18, -v10
	v_add_f32_e32 v8, v59, v8
	v_exp_f32_e32 v64, v9
	v_fma_f32 v9, v63, s18, -v10
	v_add_f32_e32 v8, v60, v8
	v_exp_f32_e32 v63, v9
	v_fma_f32 v9, v111, s18, -v10
	v_add_f32_e32 v8, v61, v8
	v_exp_f32_e32 v65, v9
	v_fma_f32 v9, v110, s18, -v10
	v_add_f32_e32 v8, v62, v8
	v_exp_f32_e32 v66, v9
	v_fma_f32 v9, v109, s18, -v10
	v_add_f32_e32 v8, v64, v8
	v_exp_f32_e32 v67, v9
	v_fma_f32 v9, v108, s18, -v10
	v_add_f32_e32 v8, v63, v8
	v_exp_f32_e32 v68, v9
	v_fma_f32 v9, v107, s18, -v10
	v_add_f32_e32 v8, v65, v8
	v_exp_f32_e32 v69, v9
	v_fma_f32 v9, v106, s18, -v10
	v_add_f32_e32 v8, v66, v8
	v_exp_f32_e32 v70, v9
	v_fma_f32 v9, v105, s18, -v10
	v_add_f32_e32 v8, v67, v8
	v_exp_f32_e32 v72, v9
	v_fma_f32 v9, v104, s18, -v10
	v_add_f32_e32 v8, v68, v8
	v_exp_f32_e32 v71, v9
	v_fma_f32 v9, v103, s18, -v10
	v_add_f32_e32 v8, v69, v8
	v_exp_f32_e32 v73, v9
	v_fma_f32 v9, v101, s18, -v10
	v_add_f32_e32 v8, v70, v8
	v_exp_f32_e32 v74, v9
	v_fma_f32 v9, v100, s18, -v10
	v_add_f32_e32 v8, v72, v8
	v_exp_f32_e32 v75, v9
	v_fma_f32 v9, v99, s18, -v10
	v_add_f32_e32 v8, v71, v8
	v_exp_f32_e32 v76, v9
	v_fma_f32 v9, v98, s18, -v10
	v_add_f32_e32 v8, v73, v8
	v_exp_f32_e32 v77, v9
	v_fma_f32 v9, v97, s18, -v10
	v_add_f32_e32 v8, v74, v8
	v_exp_f32_e32 v78, v9
	v_fma_f32 v9, v95, s18, -v10
	v_add_f32_e32 v8, v75, v8
	v_exp_f32_e32 v80, v9
	v_fma_f32 v9, v94, s18, -v10
	v_add_f32_e32 v8, v76, v8
	v_exp_f32_e32 v79, v9
	v_fma_f32 v9, v93, s18, -v10
	v_add_f32_e32 v8, v77, v8
	v_exp_f32_e32 v81, v9
	v_fma_f32 v9, v91, s18, -v10
	v_add_f32_e32 v8, v78, v8
	v_exp_f32_e32 v82, v9
	v_fma_f32 v9, v90, s18, -v10
	v_add_f32_e32 v8, v80, v8
	v_exp_f32_e32 v83, v9
	v_fma_f32 v9, v86, s18, -v10
	v_add_f32_e32 v8, v79, v8
	v_exp_f32_e32 v86, v9
	v_fma_f32 v9, v87, s18, -v10
	v_add_f32_e32 v8, v81, v8
	v_exp_f32_e32 v87, v9
	v_fma_f32 v9, v88, s18, -v10
	v_add_f32_e32 v8, v82, v8
	v_exp_f32_e32 v88, v9
	v_fma_f32 v9, v89, s18, -v10
	v_add_f32_e32 v8, v83, v8
	v_exp_f32_e32 v90, v9
	v_fma_f32 v9, v16, s18, -v10
	v_add_f32_e32 v8, v86, v8
	v_exp_f32_e32 v89, v9
	v_fma_f32 v9, v17, s18, -v10
	v_add_f32_e32 v8, v87, v8
	v_exp_f32_e32 v91, v9
	v_fma_f32 v9, v18, s18, -v10
	v_add_f32_e32 v8, v88, v8
	v_exp_f32_e32 v93, v9
	v_fma_f32 v9, v19, s18, -v10
	v_add_f32_e32 v8, v90, v8
	v_exp_f32_e32 v94, v9
	v_fma_f32 v9, v20, s18, -v10
	v_add_f32_e32 v8, v89, v8
	v_exp_f32_e32 v95, v9
	v_fma_f32 v9, v21, s18, -v10
	v_add_f32_e32 v8, v91, v8
	v_exp_f32_e32 v97, v9
	v_fma_f32 v9, v22, s18, -v10
	v_add_f32_e32 v8, v93, v8
	v_exp_f32_e32 v98, v9
	v_fma_f32 v9, v23, s18, -v10
	v_add_f32_e32 v8, v94, v8
	v_exp_f32_e32 v100, v9
	v_fma_f32 v9, v24, s18, -v10
	v_add_f32_e32 v8, v95, v8
	v_exp_f32_e32 v99, v9
	v_fma_f32 v9, v25, s18, -v10
	v_add_f32_e32 v8, v97, v8
	v_exp_f32_e32 v101, v9
	v_fma_f32 v9, v26, s18, -v10
	v_add_f32_e32 v8, v98, v8
	v_exp_f32_e32 v103, v9
	v_fma_f32 v9, v27, s18, -v10
	v_add_f32_e32 v8, v100, v8
	v_exp_f32_e32 v104, v9
	v_fma_f32 v9, v28, s18, -v10
	v_add_f32_e32 v8, v99, v8
	v_exp_f32_e32 v105, v9
	v_fma_f32 v9, v29, s18, -v10
	v_add_f32_e32 v8, v101, v8
	v_exp_f32_e32 v106, v9
	v_fma_f32 v9, v30, s18, -v10
	v_add_f32_e32 v8, v103, v8
	v_exp_f32_e32 v107, v9
	v_fma_f32 v9, v31, s18, -v10
	v_add_f32_e32 v8, v104, v8
	v_exp_f32_e32 v108, v9
	v_add_f32_e32 v8, v105, v8
	v_add_f32_e32 v8, v106, v8
	v_add_f32_e32 v8, v107, v8
	v_add_f32_e32 v8, v108, v8
	ds_bpermute_b32 v9, v112, v8
	v_fma_f32 v10, v96, s13, -v10
	v_exp_f32_e32 v10, v10
	v_cvt_pk_bf16_f32 v0, v0, v1
	v_cvt_pk_bf16_f32 v1, v2, v3
	s_waitcnt lgkmcnt(0)
	v_add_f32_e32 v8, v8, v9
	v_add_f32_e32 v96, v10, v8
	v_div_scale_f32 v8, vcc, v96, v96, 1.0
	v_rcp_f32_e32 v9, v8
	v_cvt_pk_bf16_f32 v2, v4, v5
	v_cvt_pk_bf16_f32 v3, v6, v7
	v_cvt_pk_bf16_f32 v32, v32, v33
	v_fma_f32 v10, -v8, v9, 1.0
	v_fmac_f32_e32 v9, v10, v9
	v_div_scale_f32 v10, vcc, 1.0, v96, 1.0
	v_mul_f32_e32 v11, v10, v9
	v_fma_f32 v12, -v8, v11, v10
	v_fmac_f32_e32 v11, v12, v9
	v_fma_f32 v8, -v8, v11, v10
	v_lshl_add_u32 v12, s15, 6, v139
	v_div_fmas_f32 v109, v8, v9, v11
	v_add_u32_e32 v8, v12, v157
	v_add_u32_e32 v110, 0x9000, v8
	ds_read2_b64 v[8:11], v110 offset1:2
	v_add_u32_e32 v4, v12, v158
	v_add_u32_e32 v119, 0x9000, v4
	ds_read2_b64 v[110:113], v110 offset0:4 offset1:6
	s_waitcnt lgkmcnt(1)
	v_mfma_f32_32x32x16_bf16 v[16:31], v[8:11], v[0:3], 0
	ds_read2_b64 v[4:7], v119 offset1:2
	v_cvt_pk_bf16_f32 v33, v34, v35
	v_cvt_pk_bf16_f32 v34, v36, v37
	v_cvt_pk_bf16_f32 v35, v38, v40
	v_cvt_pk_bf16_f32 v36, v39, v41
	v_cvt_pk_bf16_f32 v37, v42, v43
	v_cvt_pk_bf16_f32 v38, v44, v45
	s_waitcnt lgkmcnt(1)
	v_mfma_f32_32x32x16_bf16 v[16:31], v[110:113], v[32:35], v[16:31]
	ds_read2_b64 v[110:113], v119 offset0:4 offset1:6
	v_cvt_pk_bf16_f32 v39, v46, v48
	v_lshl_add_u32 v116, s94, 6, v139
	v_lshl_add_u32 v117, s95, 6, v139
	v_lshl_add_u32 v118, s24, 6, v139
	v_readlane_b32 s12, v254, 52
	v_readlane_b32 s13, v254, 53
	s_waitcnt lgkmcnt(1)
	v_mfma_f32_32x32x16_bf16 v[0:15], v[4:7], v[0:3], 0
	v_lshlrev_b32_e32 v130, 1, v114
	s_waitcnt lgkmcnt(0)
	v_mfma_f32_32x32x16_bf16 v[0:15], v[110:113], v[32:35], v[0:15]
	v_add_u32_e32 v32, v115, v157
	v_add_u32_e32 v40, 0x9000, v32
	ds_read2_b64 v[32:35], v40 offset1:2
	s_waitcnt lgkmcnt(0)
	v_mfma_f32_32x32x16_bf16 v[16:31], v[32:35], v[36:39], v[16:31]
	v_add_u32_e32 v32, v115, v158
	v_add_u32_e32 v41, 0x9000, v32
	ds_read2_b64 v[32:35], v41 offset1:2
	s_waitcnt lgkmcnt(0)
	v_mfma_f32_32x32x16_bf16 v[0:15], v[32:35], v[36:39], v[0:15]
	ds_read2_b64 v[32:35], v40 offset0:4 offset1:6
	v_cvt_pk_bf16_f32 v36, v47, v49
	v_cvt_pk_bf16_f32 v37, v50, v51
	v_cvt_pk_bf16_f32 v38, v52, v53
	v_cvt_pk_bf16_f32 v39, v54, v56
	s_waitcnt lgkmcnt(0)
	s_nop 0
	v_mfma_f32_32x32x16_bf16 v[16:31], v[32:35], v[36:39], v[16:31]
	ds_read2_b64 v[32:35], v41 offset0:4 offset1:6
	s_waitcnt lgkmcnt(0)
	v_mfma_f32_32x32x16_bf16 v[0:15], v[32:35], v[36:39], v[0:15]
	v_add_u32_e32 v32, v116, v157
	v_add_u32_e32 v40, 0x9000, v32
	ds_read2_b64 v[32:35], v40 offset1:2
	v_cvt_pk_bf16_f32 v36, v55, v57
	v_cvt_pk_bf16_f32 v37, v58, v59
	v_cvt_pk_bf16_f32 v38, v60, v61
	v_cvt_pk_bf16_f32 v39, v62, v64
	s_waitcnt lgkmcnt(0)
	s_nop 0
	v_mfma_f32_32x32x16_bf16 v[16:31], v[32:35], v[36:39], v[16:31]
	v_add_u32_e32 v32, v116, v158
	v_add_u32_e32 v41, 0x9000, v32
	ds_read2_b64 v[32:35], v41 offset1:2
	s_waitcnt lgkmcnt(0)
	v_mfma_f32_32x32x16_bf16 v[0:15], v[32:35], v[36:39], v[0:15]
	ds_read2_b64 v[32:35], v40 offset0:4 offset1:6
	v_cvt_pk_bf16_f32 v36, v63, v65
	v_cvt_pk_bf16_f32 v37, v66, v67
	v_cvt_pk_bf16_f32 v38, v68, v69
	v_cvt_pk_bf16_f32 v39, v70, v72
	s_waitcnt lgkmcnt(0)
	s_nop 0
	v_mfma_f32_32x32x16_bf16 v[16:31], v[32:35], v[36:39], v[16:31]
	ds_read2_b64 v[32:35], v41 offset0:4 offset1:6
	s_waitcnt lgkmcnt(0)
	v_mfma_f32_32x32x16_bf16 v[0:15], v[32:35], v[36:39], v[0:15]
	v_add_u32_e32 v32, v117, v157
	v_add_u32_e32 v40, 0x9000, v32
	ds_read2_b64 v[32:35], v40 offset1:2
	v_cvt_pk_bf16_f32 v36, v71, v73
	v_cvt_pk_bf16_f32 v37, v74, v75
	v_cvt_pk_bf16_f32 v38, v76, v77
	v_cvt_pk_bf16_f32 v39, v78, v80
	s_waitcnt lgkmcnt(0)
	s_nop 0
	v_mfma_f32_32x32x16_bf16 v[16:31], v[32:35], v[36:39], v[16:31]
	v_add_u32_e32 v32, v117, v158
	v_add_u32_e32 v41, 0x9000, v32
	ds_read2_b64 v[32:35], v41 offset1:2
	s_waitcnt lgkmcnt(0)
	v_mfma_f32_32x32x16_bf16 v[0:15], v[32:35], v[36:39], v[0:15]
	ds_read2_b64 v[32:35], v40 offset0:4 offset1:6
	v_cvt_pk_bf16_f32 v36, v79, v81
	v_cvt_pk_bf16_f32 v37, v82, v83
	v_cvt_pk_bf16_f32 v38, v86, v87
	v_cvt_pk_bf16_f32 v39, v88, v90
	s_waitcnt lgkmcnt(0)
	s_nop 0
	v_mfma_f32_32x32x16_bf16 v[16:31], v[32:35], v[36:39], v[16:31]
	ds_read2_b64 v[32:35], v41 offset0:4 offset1:6
	s_waitcnt lgkmcnt(0)
	v_mfma_f32_32x32x16_bf16 v[0:15], v[32:35], v[36:39], v[0:15]
	v_add_u32_e32 v32, v118, v157
	v_add_u32_e32 v40, 0x9000, v32
	ds_read2_b64 v[32:35], v40 offset1:2
	v_cvt_pk_bf16_f32 v36, v89, v91
	v_cvt_pk_bf16_f32 v37, v93, v94
	v_cvt_pk_bf16_f32 v38, v95, v97
	v_cvt_pk_bf16_f32 v39, v98, v100
	s_waitcnt lgkmcnt(0)
	s_nop 0
	v_mfma_f32_32x32x16_bf16 v[16:31], v[32:35], v[36:39], v[16:31]
	v_add_u32_e32 v32, v118, v158
	v_add_u32_e32 v41, 0x9000, v32
	ds_read2_b64 v[32:35], v41 offset1:2
	s_waitcnt lgkmcnt(0)
	v_mfma_f32_32x32x16_bf16 v[0:15], v[32:35], v[36:39], v[0:15]
	ds_read2_b64 v[32:35], v40 offset0:4 offset1:6
	v_cvt_pk_bf16_f32 v36, v99, v101
	v_cvt_pk_bf16_f32 v37, v103, v104
	v_cvt_pk_bf16_f32 v38, v105, v106
	v_cvt_pk_bf16_f32 v39, v107, v108
	s_waitcnt lgkmcnt(0)
	s_nop 0
	v_mfma_f32_32x32x16_bf16 v[16:31], v[32:35], v[36:39], v[16:31]
	ds_read2_b64 v[32:35], v41 offset0:4 offset1:6
	s_waitcnt lgkmcnt(0)
	v_mfma_f32_32x32x16_bf16 v[0:15], v[32:35], v[36:39], v[0:15]
	v_div_fixup_f32 v32, v109, v96, 1.0
	v_lshl_add_u64 v[34:35], s[12:13], 0, v[84:85]
	s_nop 6
	v_pk_mul_f32 v[16:17], v[16:17], v[32:33] op_sel_hi:[1,0]
	v_pk_mul_f32 v[18:19], v[18:19], v[32:33] op_sel_hi:[1,0]
	v_pk_mul_f32 v[20:21], v[20:21], v[32:33] op_sel_hi:[1,0]
	v_pk_mul_f32 v[22:23], v[22:23], v[32:33] op_sel_hi:[1,0]
	v_pk_mul_f32 v[24:25], v[24:25], v[32:33] op_sel_hi:[1,0]
	v_pk_mul_f32 v[26:27], v[26:27], v[32:33] op_sel_hi:[1,0]
	v_pk_mul_f32 v[28:29], v[28:29], v[32:33] op_sel_hi:[1,0]
	v_pk_mul_f32 v[30:31], v[30:31], v[32:33] op_sel_hi:[1,0]
	v_and_b32_e32 v152, 32, v102
	v_lshrrev_b32_e32 v152, 2, v152
	v_mov_b32_e32 v153, 0
	v_lshl_add_u64 v[200:201], v[34:35], 0, v[130:131]
	v_pk_mul_f32 v[0:1], v[0:1], v[32:33] op_sel_hi:[1,0]
	v_pk_mul_f32 v[2:3], v[2:3], v[32:33] op_sel_hi:[1,0]
	v_pk_mul_f32 v[4:5], v[4:5], v[32:33] op_sel_hi:[1,0]
	v_pk_mul_f32 v[6:7], v[6:7], v[32:33] op_sel_hi:[1,0]
	v_pk_mul_f32 v[8:9], v[8:9], v[32:33] op_sel_hi:[1,0]
	v_pk_mul_f32 v[10:11], v[10:11], v[32:33] op_sel_hi:[1,0]
	v_pk_mul_f32 v[12:13], v[12:13], v[32:33] op_sel_hi:[1,0]
	v_pk_mul_f32 v[14:15], v[14:15], v[32:33] op_sel_hi:[1,0]
	v_cvt_pk_bf16_f32 v104, v16, v17
	v_cvt_pk_bf16_f32 v105, v18, v19
	v_cvt_pk_bf16_f32 v106, v20, v21
	v_cvt_pk_bf16_f32 v107, v22, v23
	v_cvt_pk_bf16_f32 v108, v24, v25
	v_cvt_pk_bf16_f32 v109, v26, v27
	v_cvt_pk_bf16_f32 v110, v28, v29
	v_cvt_pk_bf16_f32 v111, v30, v31
	v_cvt_pk_bf16_f32 v112, v0, v1
	v_cvt_pk_bf16_f32 v113, v2, v3
	v_cvt_pk_bf16_f32 v114, v4, v5
	v_cvt_pk_bf16_f32 v115, v6, v7
	v_cvt_pk_bf16_f32 v116, v8, v9
	v_cvt_pk_bf16_f32 v117, v10, v11
	v_cvt_pk_bf16_f32 v118, v12, v13
	v_cvt_pk_bf16_f32 v119, v14, v15
	v_lshl_add_u64 v[200:201], v[200:201], 0, v[152:153]
	s_lshl_b32 s66, s23, 8
	s_sub_i32 s66, 0x12000, s66
	s_mov_b32 s56, 1
	s_mov_b32 s57, 1
	s_mov_b32 s58, 3
	s_mov_b32 s59, 3
	v_add_u32_e32 v100, v130, v152
	v_lshlrev_b32_e32 v100, 1, v100
	v_add_u32_e32 v100, s66, v100
	v_lshrrev_b32_e32 v32, 12, v84
	v_cmp_gt_u32_e64 s[70:71], 1, v32
	v_cmp_gt_u32_e64 s[94:95], 2, v32
	s_cmp_eq_u64 s[94:95], 0
	v_permlane32_swap_b32_e32 v104, v106
	v_permlane32_swap_b32_e32 v105, v107
	v_permlane32_swap_b32_e32 v108, v110
	v_permlane32_swap_b32_e32 v109, v111
	v_permlane32_swap_b32_e32 v112, v114
	v_permlane32_swap_b32_e32 v113, v115
	v_permlane32_swap_b32_e32 v116, v118
	v_permlane32_swap_b32_e32 v117, v119
	ds_read_b128 v[36:39], v100
	ds_read_b128 v[40:43], v100 offset:16
	ds_read_b128 v[44:47], v100 offset:2048
	ds_read_b128 v[48:51], v100 offset:2064
	ds_read_b128 v[52:55], v100 offset:4096
	ds_read_b128 v[56:59], v100 offset:4112
	ds_read_b128 v[60:63], v100 offset:64
	ds_read_b128 v[64:67], v100 offset:80
	ds_read_b128 v[68:71], v100 offset:2112
	ds_read_b128 v[72:75], v100 offset:2128
	ds_read_b128 v[76:79], v100 offset:4160
	ds_read_b128 v[80:83], v100 offset:4176
	s_waitcnt vmcnt(0)
	v_mov_b32_dpp v0, v182 wave_shr:1 row_mask:0xf bank_mask:0xf
	v_mov_b32_dpp v1, v183 wave_shr:1 row_mask:0xf bank_mask:0xf
	v_mov_b32_dpp v2, v184 wave_shr:1 row_mask:0xf bank_mask:0xf
	v_mov_b32_dpp v3, v185 wave_shr:1 row_mask:0xf bank_mask:0xf
	v_mov_b32_dpp v4, v186 wave_shr:1 row_mask:0xf bank_mask:0xf
	v_mov_b32_dpp v5, v187 wave_shr:1 row_mask:0xf bank_mask:0xf
	v_mov_b32_dpp v6, v188 wave_shr:1 row_mask:0xf bank_mask:0xf
	v_mov_b32_dpp v7, v189 wave_shr:1 row_mask:0xf bank_mask:0xf
	v_mov_b32_dpp v8, v202 wave_shr:1 row_mask:0xf bank_mask:0xf
	v_mov_b32_dpp v9, v203 wave_shr:1 row_mask:0xf bank_mask:0xf
	v_mov_b32_dpp v10, v204 wave_shr:1 row_mask:0xf bank_mask:0xf
	v_mov_b32_dpp v11, v205 wave_shr:1 row_mask:0xf bank_mask:0xf
	v_mov_b32_dpp v12, v206 wave_shr:1 row_mask:0xf bank_mask:0xf
	v_mov_b32_dpp v13, v207 wave_shr:1 row_mask:0xf bank_mask:0xf
	v_mov_b32_dpp v14, v208 wave_shr:1 row_mask:0xf bank_mask:0xf
	v_mov_b32_dpp v15, v209 wave_shr:1 row_mask:0xf bank_mask:0xf
	v_mov_b32_dpp v16, v0 wave_shr:1 row_mask:0xf bank_mask:0xf
	v_mov_b32_dpp v17, v1 wave_shr:1 row_mask:0xf bank_mask:0xf
	v_mov_b32_dpp v18, v2 wave_shr:1 row_mask:0xf bank_mask:0xf
	v_mov_b32_dpp v19, v3 wave_shr:1 row_mask:0xf bank_mask:0xf
	v_mov_b32_dpp v20, v4 wave_shr:1 row_mask:0xf bank_mask:0xf
	v_mov_b32_dpp v21, v5 wave_shr:1 row_mask:0xf bank_mask:0xf
	v_mov_b32_dpp v22, v6 wave_shr:1 row_mask:0xf bank_mask:0xf
	v_mov_b32_dpp v23, v7 wave_shr:1 row_mask:0xf bank_mask:0xf
	v_mov_b32_dpp v24, v8 wave_shr:1 row_mask:0xf bank_mask:0xf
	v_mov_b32_dpp v25, v9 wave_shr:1 row_mask:0xf bank_mask:0xf
	v_mov_b32_dpp v26, v10 wave_shr:1 row_mask:0xf bank_mask:0xf
	v_mov_b32_dpp v27, v11 wave_shr:1 row_mask:0xf bank_mask:0xf
	v_mov_b32_dpp v28, v12 wave_shr:1 row_mask:0xf bank_mask:0xf
	v_mov_b32_dpp v29, v13 wave_shr:1 row_mask:0xf bank_mask:0xf
	v_mov_b32_dpp v30, v14 wave_shr:1 row_mask:0xf bank_mask:0xf
	v_mov_b32_dpp v31, v15 wave_shr:1 row_mask:0xf bank_mask:0xf
	v_mov_b32_dpp v96, v144 wave_shl:1 row_mask:0xf bank_mask:0xf
	v_cndmask_b32_e64 v16, v16, v144, s[58:59]
	s_nop 0
	v_cndmask_b32_e64 v0, v0, v96, s[56:57]
	v_mov_b32_dpp v97, v145 wave_shl:1 row_mask:0xf bank_mask:0xf
	v_cndmask_b32_e64 v17, v17, v145, s[58:59]
	s_nop 0
	v_cndmask_b32_e64 v1, v1, v97, s[56:57]
	v_mov_b32_dpp v96, v146 wave_shl:1 row_mask:0xf bank_mask:0xf
	v_cndmask_b32_e64 v18, v18, v146, s[58:59]
	s_nop 0
	v_cndmask_b32_e64 v2, v2, v96, s[56:57]
	v_mov_b32_dpp v97, v147 wave_shl:1 row_mask:0xf bank_mask:0xf
	v_cndmask_b32_e64 v19, v19, v147, s[58:59]
	s_nop 0
	v_cndmask_b32_e64 v3, v3, v97, s[56:57]
	v_mov_b32_dpp v96, v148 wave_shl:1 row_mask:0xf bank_mask:0xf
	v_cndmask_b32_e64 v20, v20, v148, s[58:59]
	s_nop 0
	v_cndmask_b32_e64 v4, v4, v96, s[56:57]
	v_mov_b32_dpp v97, v149 wave_shl:1 row_mask:0xf bank_mask:0xf
	v_cndmask_b32_e64 v21, v21, v149, s[58:59]
	s_nop 0
	v_cndmask_b32_e64 v5, v5, v97, s[56:57]
	v_mov_b32_dpp v96, v150 wave_shl:1 row_mask:0xf bank_mask:0xf
	v_cndmask_b32_e64 v22, v22, v150, s[58:59]
	s_nop 0
	v_cndmask_b32_e64 v6, v6, v96, s[56:57]
	v_mov_b32_dpp v97, v151 wave_shl:1 row_mask:0xf bank_mask:0xf
	v_cndmask_b32_e64 v23, v23, v151, s[58:59]
	s_nop 0
	v_cndmask_b32_e64 v7, v7, v97, s[56:57]
	v_mov_b32_dpp v96, v192 wave_shl:1 row_mask:0xf bank_mask:0xf
	v_cndmask_b32_e64 v24, v24, v192, s[58:59]
	s_nop 0
	v_cndmask_b32_e64 v8, v8, v96, s[56:57]
	v_mov_b32_dpp v97, v193 wave_shl:1 row_mask:0xf bank_mask:0xf
	v_cndmask_b32_e64 v25, v25, v193, s[58:59]
	s_nop 0
	v_cndmask_b32_e64 v9, v9, v97, s[56:57]
	v_mov_b32_dpp v96, v194 wave_shl:1 row_mask:0xf bank_mask:0xf
	v_cndmask_b32_e64 v26, v26, v194, s[58:59]
	s_nop 0
	v_cndmask_b32_e64 v10, v10, v96, s[56:57]
	v_mov_b32_dpp v97, v195 wave_shl:1 row_mask:0xf bank_mask:0xf
	v_cndmask_b32_e64 v27, v27, v195, s[58:59]
	s_nop 0
	v_cndmask_b32_e64 v11, v11, v97, s[56:57]
	v_mov_b32_dpp v96, v196 wave_shl:1 row_mask:0xf bank_mask:0xf
	v_cndmask_b32_e64 v28, v28, v196, s[58:59]
	s_nop 0
	v_cndmask_b32_e64 v12, v12, v96, s[56:57]
	v_mov_b32_dpp v97, v197 wave_shl:1 row_mask:0xf bank_mask:0xf
	v_cndmask_b32_e64 v29, v29, v197, s[58:59]
	s_nop 0
	v_cndmask_b32_e64 v13, v13, v97, s[56:57]
	v_mov_b32_dpp v96, v198 wave_shl:1 row_mask:0xf bank_mask:0xf
	v_cndmask_b32_e64 v30, v30, v198, s[58:59]
	s_nop 0
	v_cndmask_b32_e64 v14, v14, v96, s[56:57]
	v_mov_b32_dpp v97, v199 wave_shl:1 row_mask:0xf bank_mask:0xf
	v_cndmask_b32_e64 v31, v31, v199, s[58:59]
	s_nop 0
	v_cndmask_b32_e64 v15, v15, v97, s[56:57]
	s_waitcnt lgkmcnt(6)
	s_cbranch_scc1 .Lcf_nomask0
	v_cndmask_b32_e64 v0, v0, 0, s[70:71]
	v_cndmask_b32_e64 v16, v16, 0, s[94:95]
	v_cndmask_b32_e64 v1, v1, 0, s[70:71]
	v_cndmask_b32_e64 v17, v17, 0, s[94:95]
	v_cndmask_b32_e64 v2, v2, 0, s[70:71]
	v_cndmask_b32_e64 v18, v18, 0, s[94:95]
	v_cndmask_b32_e64 v3, v3, 0, s[70:71]
	v_cndmask_b32_e64 v19, v19, 0, s[94:95]
.Lcf_nomask0:
	v_lshlrev_b32_e32 v88, 16, v16
	v_and_b32_e32 v89, 0xffff0000, v16
	v_lshlrev_b32_e32 v86, 16, v0
	v_and_b32_e32 v87, 0xffff0000, v0
	v_lshlrev_b32_e32 v34, 16, v182
	v_and_b32_e32 v35, 0xffff0000, v182
	v_lshlrev_b32_e32 v32, 16, v238
	v_and_b32_e32 v33, 0xffff0000, v238
	v_lshlrev_b32_e32 v122, 16, v222
	v_and_b32_e32 v123, 0xffff0000, v222
	v_lshlrev_b32_e32 v120, 16, v104
	v_and_b32_e32 v121, 0xffff0000, v104
	v_pk_mul_f32 v[88:89], v[36:37], v[88:89]
	v_pk_fma_f32 v[88:89], v[44:45], v[86:87], v[88:89]
	v_pk_fma_f32 v[88:89], v[52:53], v[34:35], v[88:89]
	v_pk_mul_f32 v[32:33], v[32:33], v[88:89]
	v_pk_fma_f32 v[32:33], v[122:123], v[120:121], v[32:33]
	v_cvt_pk_bf16_f32 v104, v32, v33
	v_lshlrev_b32_e32 v88, 16, v17
	v_and_b32_e32 v89, 0xffff0000, v17
	v_lshlrev_b32_e32 v86, 16, v1
	v_and_b32_e32 v87, 0xffff0000, v1
	v_lshlrev_b32_e32 v34, 16, v183
	v_and_b32_e32 v35, 0xffff0000, v183
	v_lshlrev_b32_e32 v32, 16, v239
	v_and_b32_e32 v33, 0xffff0000, v239
	v_lshlrev_b32_e32 v122, 16, v223
	v_and_b32_e32 v123, 0xffff0000, v223
	v_lshlrev_b32_e32 v120, 16, v105
	v_and_b32_e32 v121, 0xffff0000, v105
	v_pk_mul_f32 v[88:89], v[38:39], v[88:89]
	v_pk_fma_f32 v[88:89], v[46:47], v[86:87], v[88:89]
	v_pk_fma_f32 v[88:89], v[54:55], v[34:35], v[88:89]
	v_pk_mul_f32 v[32:33], v[32:33], v[88:89]
	v_pk_fma_f32 v[32:33], v[122:123], v[120:121], v[32:33]
	v_cvt_pk_bf16_f32 v105, v32, v33
	v_lshlrev_b32_e32 v88, 16, v18
	v_and_b32_e32 v89, 0xffff0000, v18
	v_lshlrev_b32_e32 v86, 16, v2
	v_and_b32_e32 v87, 0xffff0000, v2
	v_lshlrev_b32_e32 v34, 16, v184
	v_and_b32_e32 v35, 0xffff0000, v184
	v_lshlrev_b32_e32 v32, 16, v240
	v_and_b32_e32 v33, 0xffff0000, v240
	v_lshlrev_b32_e32 v122, 16, v224
	v_and_b32_e32 v123, 0xffff0000, v224
	v_lshlrev_b32_e32 v120, 16, v106
	v_and_b32_e32 v121, 0xffff0000, v106
	v_pk_mul_f32 v[88:89], v[40:41], v[88:89]
	v_pk_fma_f32 v[88:89], v[48:49], v[86:87], v[88:89]
	v_pk_fma_f32 v[88:89], v[56:57], v[34:35], v[88:89]
	v_pk_mul_f32 v[32:33], v[32:33], v[88:89]
	v_pk_fma_f32 v[32:33], v[122:123], v[120:121], v[32:33]
	v_cvt_pk_bf16_f32 v106, v32, v33
	v_lshlrev_b32_e32 v88, 16, v19
	v_and_b32_e32 v89, 0xffff0000, v19
	v_lshlrev_b32_e32 v86, 16, v3
	v_and_b32_e32 v87, 0xffff0000, v3
	v_lshlrev_b32_e32 v34, 16, v185
	v_and_b32_e32 v35, 0xffff0000, v185
	v_lshlrev_b32_e32 v32, 16, v241
	v_and_b32_e32 v33, 0xffff0000, v241
	v_lshlrev_b32_e32 v122, 16, v225
	v_and_b32_e32 v123, 0xffff0000, v225
	v_lshlrev_b32_e32 v120, 16, v107
	v_and_b32_e32 v121, 0xffff0000, v107
	v_pk_mul_f32 v[88:89], v[42:43], v[88:89]
	v_pk_fma_f32 v[88:89], v[50:51], v[86:87], v[88:89]
	v_pk_fma_f32 v[88:89], v[58:59], v[34:35], v[88:89]
	v_pk_mul_f32 v[32:33], v[32:33], v[88:89]
	v_pk_fma_f32 v[32:33], v[122:123], v[120:121], v[32:33]
	v_cvt_pk_bf16_f32 v107, v32, v33
	global_store_dwordx4 v[200:201], v[104:107], off
	ds_read_b128 v[36:39], v100 offset:128
	ds_read_b128 v[40:43], v100 offset:144
	ds_read_b128 v[44:47], v100 offset:2176
	ds_read_b128 v[48:51], v100 offset:2192
	ds_read_b128 v[52:55], v100 offset:4224
	ds_read_b128 v[56:59], v100 offset:4240
	s_waitcnt lgkmcnt(6)
	s_cbranch_scc1 .Lcf_nomask1
	v_cndmask_b32_e64 v4, v4, 0, s[70:71]
	v_cndmask_b32_e64 v20, v20, 0, s[94:95]
	v_cndmask_b32_e64 v5, v5, 0, s[70:71]
	v_cndmask_b32_e64 v21, v21, 0, s[94:95]
	v_cndmask_b32_e64 v6, v6, 0, s[70:71]
	v_cndmask_b32_e64 v22, v22, 0, s[94:95]
	v_cndmask_b32_e64 v7, v7, 0, s[70:71]
	v_cndmask_b32_e64 v23, v23, 0, s[94:95]
.Lcf_nomask1:
	v_lshlrev_b32_e32 v88, 16, v20
	v_and_b32_e32 v89, 0xffff0000, v20
	v_lshlrev_b32_e32 v86, 16, v4
	v_and_b32_e32 v87, 0xffff0000, v4
	v_lshlrev_b32_e32 v34, 16, v186
	v_and_b32_e32 v35, 0xffff0000, v186
	v_lshlrev_b32_e32 v32, 16, v242
	v_and_b32_e32 v33, 0xffff0000, v242
	v_lshlrev_b32_e32 v122, 16, v226
	v_and_b32_e32 v123, 0xffff0000, v226
	v_lshlrev_b32_e32 v120, 16, v108
	v_and_b32_e32 v121, 0xffff0000, v108
	v_pk_mul_f32 v[88:89], v[60:61], v[88:89]
	v_pk_fma_f32 v[88:89], v[68:69], v[86:87], v[88:89]
	v_pk_fma_f32 v[88:89], v[76:77], v[34:35], v[88:89]
	v_pk_mul_f32 v[32:33], v[32:33], v[88:89]
	v_pk_fma_f32 v[32:33], v[122:123], v[120:121], v[32:33]
	v_cvt_pk_bf16_f32 v108, v32, v33
	v_lshlrev_b32_e32 v88, 16, v21
	v_and_b32_e32 v89, 0xffff0000, v21
	v_lshlrev_b32_e32 v86, 16, v5
	v_and_b32_e32 v87, 0xffff0000, v5
	v_lshlrev_b32_e32 v34, 16, v187
	v_and_b32_e32 v35, 0xffff0000, v187
	v_lshlrev_b32_e32 v32, 16, v243
	v_and_b32_e32 v33, 0xffff0000, v243
	v_lshlrev_b32_e32 v122, 16, v227
	v_and_b32_e32 v123, 0xffff0000, v227
	v_lshlrev_b32_e32 v120, 16, v109
	v_and_b32_e32 v121, 0xffff0000, v109
	v_pk_mul_f32 v[88:89], v[62:63], v[88:89]
	v_pk_fma_f32 v[88:89], v[70:71], v[86:87], v[88:89]
	v_pk_fma_f32 v[88:89], v[78:79], v[34:35], v[88:89]
	v_pk_mul_f32 v[32:33], v[32:33], v[88:89]
	v_pk_fma_f32 v[32:33], v[122:123], v[120:121], v[32:33]
	v_cvt_pk_bf16_f32 v109, v32, v33
	v_lshlrev_b32_e32 v88, 16, v22
	v_and_b32_e32 v89, 0xffff0000, v22
	v_lshlrev_b32_e32 v86, 16, v6
	v_and_b32_e32 v87, 0xffff0000, v6
	v_lshlrev_b32_e32 v34, 16, v188
	v_and_b32_e32 v35, 0xffff0000, v188
	v_lshlrev_b32_e32 v32, 16, v244
	v_and_b32_e32 v33, 0xffff0000, v244
	v_lshlrev_b32_e32 v122, 16, v228
	v_and_b32_e32 v123, 0xffff0000, v228
	v_lshlrev_b32_e32 v120, 16, v110
	v_and_b32_e32 v121, 0xffff0000, v110
	v_pk_mul_f32 v[88:89], v[64:65], v[88:89]
	v_pk_fma_f32 v[88:89], v[72:73], v[86:87], v[88:89]
	v_pk_fma_f32 v[88:89], v[80:81], v[34:35], v[88:89]
	v_pk_mul_f32 v[32:33], v[32:33], v[88:89]
	v_pk_fma_f32 v[32:33], v[122:123], v[120:121], v[32:33]
	v_cvt_pk_bf16_f32 v110, v32, v33
	v_lshlrev_b32_e32 v88, 16, v23
	v_and_b32_e32 v89, 0xffff0000, v23
	v_lshlrev_b32_e32 v86, 16, v7
	v_and_b32_e32 v87, 0xffff0000, v7
	v_lshlrev_b32_e32 v34, 16, v189
	v_and_b32_e32 v35, 0xffff0000, v189
	v_lshlrev_b32_e32 v32, 16, v245
	v_and_b32_e32 v33, 0xffff0000, v245
	v_lshlrev_b32_e32 v122, 16, v229
	v_and_b32_e32 v123, 0xffff0000, v229
	v_lshlrev_b32_e32 v120, 16, v111
	v_and_b32_e32 v121, 0xffff0000, v111
	v_pk_mul_f32 v[88:89], v[66:67], v[88:89]
	v_pk_fma_f32 v[88:89], v[74:75], v[86:87], v[88:89]
	v_pk_fma_f32 v[88:89], v[82:83], v[34:35], v[88:89]
	v_pk_mul_f32 v[32:33], v[32:33], v[88:89]
	v_pk_fma_f32 v[32:33], v[122:123], v[120:121], v[32:33]
	v_cvt_pk_bf16_f32 v111, v32, v33
	global_store_dwordx4 v[200:201], v[108:111], off offset:32
	ds_read_b128 v[60:63], v100 offset:192
	ds_read_b128 v[64:67], v100 offset:208
	ds_read_b128 v[68:71], v100 offset:2240
	ds_read_b128 v[72:75], v100 offset:2256
	ds_read_b128 v[76:79], v100 offset:4288
	ds_read_b128 v[80:83], v100 offset:4304
	s_waitcnt lgkmcnt(6)
	s_cbranch_scc1 .Lcf_nomask2
	v_cndmask_b32_e64 v8, v8, 0, s[70:71]
	v_cndmask_b32_e64 v24, v24, 0, s[94:95]
	v_cndmask_b32_e64 v9, v9, 0, s[70:71]
	v_cndmask_b32_e64 v25, v25, 0, s[94:95]
	v_cndmask_b32_e64 v10, v10, 0, s[70:71]
	v_cndmask_b32_e64 v26, v26, 0, s[94:95]
	v_cndmask_b32_e64 v11, v11, 0, s[70:71]
	v_cndmask_b32_e64 v27, v27, 0, s[94:95]
.Lcf_nomask2:
	v_lshlrev_b32_e32 v88, 16, v24
	v_and_b32_e32 v89, 0xffff0000, v24
	v_lshlrev_b32_e32 v86, 16, v8
	v_and_b32_e32 v87, 0xffff0000, v8
	v_lshlrev_b32_e32 v34, 16, v202
	v_and_b32_e32 v35, 0xffff0000, v202
	v_lshlrev_b32_e32 v32, 16, v246
	v_and_b32_e32 v33, 0xffff0000, v246
	v_lshlrev_b32_e32 v122, 16, v230
	v_and_b32_e32 v123, 0xffff0000, v230
	v_lshlrev_b32_e32 v120, 16, v112
	v_and_b32_e32 v121, 0xffff0000, v112
	v_pk_mul_f32 v[88:89], v[36:37], v[88:89]
	v_pk_fma_f32 v[88:89], v[44:45], v[86:87], v[88:89]
	v_pk_fma_f32 v[88:89], v[52:53], v[34:35], v[88:89]
	v_pk_mul_f32 v[32:33], v[32:33], v[88:89]
	v_pk_fma_f32 v[32:33], v[122:123], v[120:121], v[32:33]
	v_cvt_pk_bf16_f32 v112, v32, v33
	v_lshlrev_b32_e32 v88, 16, v25
	v_and_b32_e32 v89, 0xffff0000, v25
	v_lshlrev_b32_e32 v86, 16, v9
	v_and_b32_e32 v87, 0xffff0000, v9
	v_lshlrev_b32_e32 v34, 16, v203
	v_and_b32_e32 v35, 0xffff0000, v203
	v_lshlrev_b32_e32 v32, 16, v247
	v_and_b32_e32 v33, 0xffff0000, v247
	v_lshlrev_b32_e32 v122, 16, v231
	v_and_b32_e32 v123, 0xffff0000, v231
	v_lshlrev_b32_e32 v120, 16, v113
	v_and_b32_e32 v121, 0xffff0000, v113
	v_pk_mul_f32 v[88:89], v[38:39], v[88:89]
	v_pk_fma_f32 v[88:89], v[46:47], v[86:87], v[88:89]
	v_pk_fma_f32 v[88:89], v[54:55], v[34:35], v[88:89]
	v_pk_mul_f32 v[32:33], v[32:33], v[88:89]
	v_pk_fma_f32 v[32:33], v[122:123], v[120:121], v[32:33]
	v_cvt_pk_bf16_f32 v113, v32, v33
	v_lshlrev_b32_e32 v88, 16, v26
	v_and_b32_e32 v89, 0xffff0000, v26
	v_lshlrev_b32_e32 v86, 16, v10
	v_and_b32_e32 v87, 0xffff0000, v10
	v_lshlrev_b32_e32 v34, 16, v204
	v_and_b32_e32 v35, 0xffff0000, v204
	v_lshlrev_b32_e32 v32, 16, v248
	v_and_b32_e32 v33, 0xffff0000, v248
	v_lshlrev_b32_e32 v122, 16, v232
	v_and_b32_e32 v123, 0xffff0000, v232
	v_lshlrev_b32_e32 v120, 16, v114
	v_and_b32_e32 v121, 0xffff0000, v114
	v_pk_mul_f32 v[88:89], v[40:41], v[88:89]
	v_pk_fma_f32 v[88:89], v[48:49], v[86:87], v[88:89]
	v_pk_fma_f32 v[88:89], v[56:57], v[34:35], v[88:89]
	v_pk_mul_f32 v[32:33], v[32:33], v[88:89]
	v_pk_fma_f32 v[32:33], v[122:123], v[120:121], v[32:33]
	v_cvt_pk_bf16_f32 v114, v32, v33
	v_lshlrev_b32_e32 v88, 16, v27
	v_and_b32_e32 v89, 0xffff0000, v27
	v_lshlrev_b32_e32 v86, 16, v11
	v_and_b32_e32 v87, 0xffff0000, v11
	v_lshlrev_b32_e32 v34, 16, v205
	v_and_b32_e32 v35, 0xffff0000, v205
	v_lshlrev_b32_e32 v32, 16, v249
	v_and_b32_e32 v33, 0xffff0000, v249
	v_lshlrev_b32_e32 v122, 16, v233
	v_and_b32_e32 v123, 0xffff0000, v233
	v_lshlrev_b32_e32 v120, 16, v115
	v_and_b32_e32 v121, 0xffff0000, v115
	v_pk_mul_f32 v[88:89], v[42:43], v[88:89]
	v_pk_fma_f32 v[88:89], v[50:51], v[86:87], v[88:89]
	v_pk_fma_f32 v[88:89], v[58:59], v[34:35], v[88:89]
	v_pk_mul_f32 v[32:33], v[32:33], v[88:89]
	v_pk_fma_f32 v[32:33], v[122:123], v[120:121], v[32:33]
	v_cvt_pk_bf16_f32 v115, v32, v33
	global_store_dwordx4 v[200:201], v[112:115], off offset:64
	s_waitcnt lgkmcnt(0)
	s_cbranch_scc1 .Lcf_nomask3
	v_cndmask_b32_e64 v12, v12, 0, s[70:71]
	v_cndmask_b32_e64 v28, v28, 0, s[94:95]
	v_cndmask_b32_e64 v13, v13, 0, s[70:71]
	v_cndmask_b32_e64 v29, v29, 0, s[94:95]
	v_cndmask_b32_e64 v14, v14, 0, s[70:71]
	v_cndmask_b32_e64 v30, v30, 0, s[94:95]
	v_cndmask_b32_e64 v15, v15, 0, s[70:71]
	v_cndmask_b32_e64 v31, v31, 0, s[94:95]
.Lcf_nomask3:
	v_lshlrev_b32_e32 v88, 16, v28
	v_and_b32_e32 v89, 0xffff0000, v28
	v_lshlrev_b32_e32 v86, 16, v12
	v_and_b32_e32 v87, 0xffff0000, v12
	v_lshlrev_b32_e32 v34, 16, v206
	v_and_b32_e32 v35, 0xffff0000, v206
	v_lshlrev_b32_e32 v32, 16, v250
	v_and_b32_e32 v33, 0xffff0000, v250
	v_lshlrev_b32_e32 v122, 16, v234
	v_and_b32_e32 v123, 0xffff0000, v234
	v_lshlrev_b32_e32 v120, 16, v116
	v_and_b32_e32 v121, 0xffff0000, v116
	v_pk_mul_f32 v[88:89], v[60:61], v[88:89]
	v_pk_fma_f32 v[88:89], v[68:69], v[86:87], v[88:89]
	v_pk_fma_f32 v[88:89], v[76:77], v[34:35], v[88:89]
	v_pk_mul_f32 v[32:33], v[32:33], v[88:89]
	v_pk_fma_f32 v[32:33], v[122:123], v[120:121], v[32:33]
	v_cvt_pk_bf16_f32 v116, v32, v33
	v_lshlrev_b32_e32 v88, 16, v29
	v_and_b32_e32 v89, 0xffff0000, v29
	v_lshlrev_b32_e32 v86, 16, v13
	v_and_b32_e32 v87, 0xffff0000, v13
	v_lshlrev_b32_e32 v34, 16, v207
	v_and_b32_e32 v35, 0xffff0000, v207
	v_lshlrev_b32_e32 v32, 16, v251
	v_and_b32_e32 v33, 0xffff0000, v251
	v_lshlrev_b32_e32 v122, 16, v235
	v_and_b32_e32 v123, 0xffff0000, v235
	v_lshlrev_b32_e32 v120, 16, v117
	v_and_b32_e32 v121, 0xffff0000, v117
	v_pk_mul_f32 v[88:89], v[62:63], v[88:89]
	v_pk_fma_f32 v[88:89], v[70:71], v[86:87], v[88:89]
	v_pk_fma_f32 v[88:89], v[78:79], v[34:35], v[88:89]
	v_pk_mul_f32 v[32:33], v[32:33], v[88:89]
	v_pk_fma_f32 v[32:33], v[122:123], v[120:121], v[32:33]
	v_cvt_pk_bf16_f32 v117, v32, v33
	v_lshlrev_b32_e32 v88, 16, v30
	v_and_b32_e32 v89, 0xffff0000, v30
	v_lshlrev_b32_e32 v86, 16, v14
	v_and_b32_e32 v87, 0xffff0000, v14
	v_lshlrev_b32_e32 v34, 16, v208
	v_and_b32_e32 v35, 0xffff0000, v208
	v_lshlrev_b32_e32 v32, 16, v252
	v_and_b32_e32 v33, 0xffff0000, v252
	v_lshlrev_b32_e32 v122, 16, v236
	v_and_b32_e32 v123, 0xffff0000, v236
	v_lshlrev_b32_e32 v120, 16, v118
	v_and_b32_e32 v121, 0xffff0000, v118
	v_pk_mul_f32 v[88:89], v[64:65], v[88:89]
	v_pk_fma_f32 v[88:89], v[72:73], v[86:87], v[88:89]
	v_pk_fma_f32 v[88:89], v[80:81], v[34:35], v[88:89]
	v_pk_mul_f32 v[32:33], v[32:33], v[88:89]
	v_pk_fma_f32 v[32:33], v[122:123], v[120:121], v[32:33]
	v_cvt_pk_bf16_f32 v118, v32, v33
	v_lshlrev_b32_e32 v88, 16, v31
	v_and_b32_e32 v89, 0xffff0000, v31
	v_lshlrev_b32_e32 v86, 16, v15
	v_and_b32_e32 v87, 0xffff0000, v15
	v_lshlrev_b32_e32 v34, 16, v209
	v_and_b32_e32 v35, 0xffff0000, v209
	v_lshlrev_b32_e32 v32, 16, v253
	v_and_b32_e32 v33, 0xffff0000, v253
	v_lshlrev_b32_e32 v122, 16, v237
	v_and_b32_e32 v123, 0xffff0000, v237
	v_lshlrev_b32_e32 v120, 16, v119
	v_and_b32_e32 v121, 0xffff0000, v119
	v_pk_mul_f32 v[88:89], v[66:67], v[88:89]
	v_pk_fma_f32 v[88:89], v[74:75], v[86:87], v[88:89]
	v_pk_fma_f32 v[88:89], v[82:83], v[34:35], v[88:89]
	v_pk_mul_f32 v[32:33], v[32:33], v[88:89]
	v_pk_fma_f32 v[32:33], v[122:123], v[120:121], v[32:33]
	v_cvt_pk_bf16_f32 v119, v32, v33
	global_store_dwordx4 v[200:201], v[116:119], off offset:96


	s_mov_b64 s[12:13], 0
